# diff attention loops: LDS-DMA addressing moved from VALU to SALU (saddr-form global_load_lds, hoisted per-lane offsets, M0 from SGPR adds)
# speedup vs baseline: 1.0198x; 1.0198x over previous
.LBB0_158:
	v_add_f32_e32 v111, 0, v123
	v_add_f32_e32 v119, 0, v125
	v_add_f32_e32 v111, v126, v111
	v_add_f32_e32 v119, v127, v119
	v_exp_f32_e32 v127, v64
	v_exp_f32_e32 v126, v80
	v_exp_f32_e32 v65, v65
	v_exp_f32_e32 v64, v81
	v_add_f32_e32 v111, v130, v111
	v_add_f32_e32 v119, v131, v119
	v_exp_f32_e32 v131, v66
	v_exp_f32_e32 v130, v82
	v_exp_f32_e32 v67, v67
	v_exp_f32_e32 v66, v83
	v_pk_add_f32 v[80:81], v[126:127], 0 op_sel_hi:[1,0]
	v_exp_f32_e32 v83, v68
	v_exp_f32_e32 v82, v84
	v_add_f32_e32 v111, v132, v111
	v_add_f32_e32 v119, v133, v119
	v_pk_add_f32 v[80:81], v[64:65], v[80:81]
	v_exp_f32_e32 v133, v69
	v_exp_f32_e32 v132, v85
	v_add_f32_e32 v111, v134, v111
	v_pk_add_f32 v[80:81], v[130:131], v[80:81]
	v_exp_f32_e32 v85, v70
	v_exp_f32_e32 v84, v86
	v_add_f32_e32 v119, v135, v119
	v_add_f32_e32 v111, v140, v111
	v_pk_add_f32 v[80:81], v[66:67], v[80:81]
	v_exp_f32_e32 v135, v71
	v_exp_f32_e32 v134, v87
	v_add_f32_e32 v111, v142, v111
	v_exp_f32_e32 v87, v72
	v_exp_f32_e32 v86, v88
	v_pk_add_f32 v[68:69], v[82:83], v[80:81]
	v_add_f32_e32 v119, v141, v119
	v_add_f32_e32 v111, v143, v111
	v_exp_f32_e32 v141, v73
	v_exp_f32_e32 v140, v89
	v_pk_add_f32 v[68:69], v[132:133], v[68:69]
	v_add_f32_e32 v111, v146, v111
	v_exp_f32_e32 v89, v74
	v_exp_f32_e32 v88, v90
	v_pk_add_f32 v[68:69], v[84:85], v[68:69]
	v_add_f32_e32 v111, v145, v111
	v_exp_f32_e32 v143, v75
	v_exp_f32_e32 v142, v91
	v_pk_add_f32 v[68:69], v[134:135], v[68:69]
	v_add_f32_e32 v111, v144, v111
	v_exp_f32_e32 v91, v76
	v_exp_f32_e32 v90, v92
	v_pk_add_f32 v[68:69], v[86:87], v[68:69]
	v_add_f32_e32 v111, v149, v111
	v_exp_f32_e32 v145, v77
	v_exp_f32_e32 v144, v93
	v_pk_add_f32 v[68:69], v[140:141], v[68:69]
	v_add_f32_e32 v111, v148, v111
	v_exp_f32_e32 v93, v78
	v_exp_f32_e32 v92, v94
	v_pk_add_f32 v[68:69], v[88:89], v[68:69]
	v_add_f32_e32 v111, v147, v111
	v_exp_f32_e32 v147, v79
	v_exp_f32_e32 v146, v95
	v_pk_add_f32 v[68:69], v[142:143], v[68:69]
	v_cvt_pk_bf16_f32 v76, v127, v65
	v_pk_add_f32 v[68:69], v[90:91], v[68:69]
	v_cvt_pk_bf16_f32 v78, v83, v133
	v_pk_add_f32 v[68:69], v[144:145], v[68:69]
	v_cvt_pk_bf16_f32 v79, v85, v135
	v_pk_add_f32 v[68:69], v[92:93], v[68:69]
	v_cvt_pk_bf16_f32 v70, v82, v132
	v_pk_add_f32 v[68:69], v[146:147], v[68:69]
	v_cvt_pk_bf16_f32 v71, v84, v134
	v_add_f32_e32 v80, v68, v69
	v_cvt_pk_bf16_f32 v68, v126, v64
	v_cvt_pk_bf16_f32 v72, v87, v141
	v_cvt_pk_bf16_f32 v73, v89, v143
	v_cvt_pk_bf16_f32 v64, v86, v140
	v_cvt_pk_bf16_f32 v65, v88, v142
	ds_read_b128 v[82:85], v122 offset:16384
	ds_read_b128 v[86:89], v122 offset:20480
	v_cvt_pk_bf16_f32 v77, v131, v67
	v_cvt_pk_bf16_f32 v74, v91, v145
	v_cvt_pk_bf16_f32 v75, v93, v147
	s_waitcnt lgkmcnt(0)
	v_mfma_f32_32x32x16_bf16 v[0:15], v[82:85], v[76:79], v[0:15]
	ds_read_b128 v[82:85], v121 offset:20480
	v_cvt_pk_bf16_f32 v69, v130, v66
	v_add_f32_e32 v119, v154, v119
	v_add_f32_e32 v119, v153, v119
	v_add_f32_e32 v119, v152, v119
	v_add_f32_e32 v119, v156, v119
	v_add_f32_e32 v119, v155, v119
	v_mfma_f32_32x32x16_bf16 v[16:31], v[86:89], v[76:79], v[16:31]
	ds_read_b128 v[76:79], v121 offset:16384
	v_cvt_pk_bf16_f32 v66, v90, v144
	v_cvt_pk_bf16_f32 v67, v92, v146
	v_add_f32_e32 v119, v159, v119
	v_add_f32_e32 v119, v158, v119
	v_add_f32_e32 v119, v157, v119
	v_add_f32_e32 v111, v151, v111
	s_waitcnt lgkmcnt(0)
	v_mfma_f32_32x32x16_bf16 v[0:15], v[76:79], v[72:75], v[0:15]
	ds_read_b128 v[76:79], v120 offset:20480
	v_add_f32_e32 v119, v161, v119
	v_add_f32_e32 v111, v150, v111
	v_add_f32_e32 v119, v160, v119
	v_add_f32_e32 v111, v119, v111
	s_sub_i32 s11, 0x82, s13
	v_add_f32_e32 v111, 0, v111
	v_mfma_f32_32x32x16_bf16 v[16:31], v[82:85], v[72:75], v[16:31]
	ds_read_b128 v[72:75], v120 offset:16384
	s_cmp_lt_u32 s12, 64
	v_add_f32_e32 v175, v111, v80
	s_cselect_b64 s[42:43], -1, 0
	s_cmp_gt_u32 s12, 63
	s_waitcnt lgkmcnt(0)
	v_mfma_f32_32x32x16_bf16 v[0:15], v[72:75], v[68:71], v[0:15]
	ds_read_b128 v[72:75], v110 offset:20480
	v_mfma_f32_32x32x16_bf16 v[16:31], v[76:79], v[68:71], v[16:31]
	ds_read_b128 v[68:71], v110 offset:16384
	s_waitcnt vmcnt(0)
	s_waitcnt vmcnt(0) lgkmcnt(0)
	s_barrier
	v_mfma_f32_32x32x16_bf16 v[0:15], v[68:71], v[64:67], v[0:15]
	v_mfma_f32_32x32x16_bf16 v[16:31], v[72:75], v[64:67], v[16:31]
	s_cbranch_scc1 .LBB0_173
	s_mov_b64 s[100:101], s[50:51]
	v_readfirstlane_b32 s98, v109
	v_readfirstlane_b32 s99, v113
	v_lshlrev_b32_e32 v222, 1, v192
	v_lshlrev_b32_e32 v227, 1, v104
	v_lshlrev_b32_e32 v228, 1, v106
	v_lshl_add_u64 v[110:111], v[192:193], 1, s[50:51]
	s_mov_b32 s50, 2
	s_movk_i32 s12, 0x3000
	s_mov_b32 s10, 0
	s_movk_i32 s2, 0x6000
.LBB0_160:
	s_add_i32 s69, s13, s50
	s_add_i32 s70, s69, 2
	s_lshl_b64 vcc, s[70:71], 12
	s_add_u32 vcc_lo, s100, vcc_lo
	s_addc_u32 vcc_hi, s101, vcc_hi
	s_add_i32 s3, s12, 32
	s_add_i32 s8, s3, s98
	s_mov_b32 m0, s8
	s_add_i32 s3, s3, s99
	global_load_lds_dwordx4 v222, vcc
	s_lshl_b64 vcc, s[70:71], 7
	s_add_u32 vcc_lo, s19, vcc_lo
	s_addc_u32 vcc_hi, s5, vcc_hi
	s_add_i32 m0, s8, 0x1000
	s_addk_i32 s3, 0x1000
	global_load_lds_dwordx4 v227, vcc
	s_mov_b32 m0, s3
	s_mov_b32 s51, s10
	global_load_lds_dwordx4 v228, vcc
	s_add_i32 s8, s51, 32
	v_add_u32_e32 v64, s8, v115
	s_mov_b32 s10, s2
	s_mov_b64 s[2:3], -1
	s_and_b64 vcc, exec, s[28:29]
	v_add_u32_e32 v120, v64, v116
	v_add_u32_e32 v119, v64, v117
	s_cbranch_vccnz .LBB0_162
	ds_read_b128 v[64:67], v120
	ds_read_b128 v[130:133], v119
	s_mov_b64 s[2:3], 0
	s_waitcnt lgkmcnt(0)
	v_mfma_f32_32x32x16_bf16 v[80:95], v[64:67], v[100:103], 0
	ds_read_b128 v[64:67], v120 offset:2048
	v_mfma_f32_32x32x16_bf16 v[80:95], v[130:133], v[96:99], v[80:95]
	ds_read_b128 v[130:133], v119 offset:2048
	s_waitcnt lgkmcnt(0)
	v_mfma_f32_32x32x16_bf16 v[64:79], v[64:67], v[100:103], 0
	v_mfma_f32_32x32x16_bf16 v[64:79], v[130:133], v[96:99], v[64:79]

.LBB0_167:
	v_exp_f32_e32 v142, v56
	v_add_u32_e32 v56, s10, v118
	v_exp_f32_e32 v130, v52
	v_add_u32_e32 v52, v56, v114
	v_exp_f32_e32 v119, v48
	v_exp_f32_e32 v121, v49
	v_exp_f32_e32 v123, v50
	v_exp_f32_e32 v126, v51
	v_exp_f32_e32 v132, v53
	v_exp_f32_e32 v134, v54
	v_exp_f32_e32 v140, v55
	ds_read_b128 v[48:51], v52 offset:4096
	ds_read_b128 v[52:55], v52 offset:8192
	v_exp_f32_e32 v151, v44
	v_exp_f32_e32 v153, v45
	v_exp_f32_e32 v155, v46
	v_exp_f32_e32 v157, v47
	v_cvt_pk_bf16_f32 v44, v119, v121
	v_cvt_pk_bf16_f32 v45, v123, v126
	v_cvt_pk_bf16_f32 v46, v130, v132
	v_cvt_pk_bf16_f32 v47, v134, v140
	v_exp_f32_e32 v144, v57
	v_exp_f32_e32 v146, v58
	s_waitcnt lgkmcnt(0)
	v_mfma_f32_32x32x16_bf16 v[0:15], v[48:51], v[44:47], v[0:15]
	v_add_u32_e32 v48, v56, v124
	v_exp_f32_e32 v148, v59
	v_exp_f32_e32 v150, v60
	v_exp_f32_e32 v152, v61
	v_exp_f32_e32 v154, v62
	v_exp_f32_e32 v156, v63
	v_exp_f32_e32 v143, v40
	v_mfma_f32_32x32x16_bf16 v[16:31], v[52:55], v[44:47], v[16:31]
	ds_read_b128 v[44:47], v48 offset:4096
	ds_read_b128 v[48:51], v48 offset:8192
	v_exp_f32_e32 v145, v41
	v_exp_f32_e32 v147, v42
	v_exp_f32_e32 v149, v43
	v_cvt_pk_bf16_f32 v40, v142, v144
	v_cvt_pk_bf16_f32 v41, v146, v148
	v_cvt_pk_bf16_f32 v42, v150, v152
	v_cvt_pk_bf16_f32 v43, v154, v156
	v_exp_f32_e32 v120, v32
	v_exp_f32_e32 v122, v33
	s_waitcnt lgkmcnt(0)
	v_mfma_f32_32x32x16_bf16 v[0:15], v[44:47], v[40:43], v[0:15]
	v_add_u32_e32 v44, v56, v128
	v_exp_f32_e32 v125, v34
	v_exp_f32_e32 v127, v35
	v_exp_f32_e32 v131, v36
	v_exp_f32_e32 v133, v37
	v_exp_f32_e32 v135, v38
	v_exp_f32_e32 v141, v39
	v_mfma_f32_32x32x16_bf16 v[16:31], v[48:51], v[40:43], v[16:31]
	ds_read_b128 v[40:43], v44 offset:4096
	ds_read_b128 v[44:47], v44 offset:8192
	v_cvt_pk_bf16_f32 v36, v120, v122
	v_cvt_pk_bf16_f32 v37, v125, v127
	v_cvt_pk_bf16_f32 v38, v131, v133
	v_cvt_pk_bf16_f32 v39, v135, v141
	s_add_i32 s70, s69, 3
	s_lshl_b64 s[2:3], s[70:71], 12
	s_waitcnt lgkmcnt(0)
	v_mfma_f32_32x32x16_bf16 v[0:15], v[40:43], v[36:39], v[0:15]
	v_add_u32_e32 v40, v56, v129
	v_cvt_pk_bf16_f32 v32, v143, v145
	v_cvt_pk_bf16_f32 v33, v147, v149
	v_cvt_pk_bf16_f32 v34, v151, v153
	v_cvt_pk_bf16_f32 v35, v155, v157
	s_cmp_lg_u32 32, -1
	v_mfma_f32_32x32x16_bf16 v[16:31], v[44:47], v[36:39], v[16:31]
	ds_read_b128 v[36:39], v40 offset:4096
	ds_read_b128 v[40:43], v40 offset:8192
	s_waitcnt vmcnt(0)
	s_waitcnt vmcnt(0) lgkmcnt(0)
	s_barrier
	v_mfma_f32_32x32x16_bf16 v[0:15], v[36:39], v[32:35], v[0:15]
	v_mfma_f32_32x32x16_bf16 v[16:31], v[40:43], v[32:35], v[16:31]
	s_add_u32 s2, s100, s2
	s_addc_u32 s3, s101, s3
	s_add_i32 s69, s10, 32
	s_add_i32 vcc_lo, s69, s98
	s_mov_b32 m0, vcc_lo
	s_add_i32 vcc_hi, s69, s99
	global_load_lds_dwordx4 v222, s[2:3]
	s_lshl_b64 s[2:3], s[70:71], 7
	s_add_u32 s2, s19, s2
	s_addc_u32 s3, s5, s3
	s_add_i32 m0, vcc_lo, 0x1000
	s_add_i32 s69, s12, 32
	global_load_lds_dwordx4 v227, s[2:3]
	s_add_i32 m0, vcc_hi, 0x1000
	s_nop 0
	global_load_lds_dwordx4 v228, s[2:3]
	v_add_u32_e32 v32, s69, v115
	s_mov_b64 s[2:3], -1
	s_and_b64 vcc, exec, s[28:29]
	v_add_u32_e32 v159, v32, v116
	v_add_u32_e32 v158, v32, v117
	s_cbranch_vccnz .LBB0_169
	ds_read_b128 v[32:35], v159
	ds_read_b128 v[160:163], v158
	s_mov_b64 s[2:3], 0
	s_waitcnt lgkmcnt(0)
	v_mfma_f32_32x32x16_bf16 v[48:63], v[32:35], v[100:103], 0
	ds_read_b128 v[32:35], v159 offset:2048
	v_mfma_f32_32x32x16_bf16 v[48:63], v[160:163], v[96:99], v[48:63]
	ds_read_b128 v[160:163], v158 offset:2048
	s_waitcnt lgkmcnt(0)
	v_mfma_f32_32x32x16_bf16 v[32:47], v[32:35], v[100:103], 0
	v_mfma_f32_32x32x16_bf16 v[32:47], v[160:163], v[96:99], v[32:47]

.LBB0_189:
	v_add_f32_e32 v152, 0, v152
	v_add_f32_e32 v153, 0, v153
	v_add_f32_e32 v152, v154, v152
	v_add_f32_e32 v153, v155, v153
	v_exp_f32_e32 v155, v96
	v_exp_f32_e32 v154, v112
	v_exp_f32_e32 v97, v97
	v_exp_f32_e32 v96, v113
	v_add_f32_e32 v152, v156, v152
	v_add_f32_e32 v153, v157, v153
	v_exp_f32_e32 v157, v98
	v_exp_f32_e32 v156, v114
	v_exp_f32_e32 v99, v99
	v_exp_f32_e32 v98, v115
	v_pk_add_f32 v[112:113], v[154:155], 0 op_sel_hi:[1,0]
	v_exp_f32_e32 v115, v100
	v_exp_f32_e32 v114, v116
	v_add_f32_e32 v152, v158, v152
	v_add_f32_e32 v153, v159, v153
	v_pk_add_f32 v[112:113], v[96:97], v[112:113]
	v_exp_f32_e32 v159, v101
	v_exp_f32_e32 v158, v117
	v_pk_add_f32 v[112:113], v[156:157], v[112:113]
	v_exp_f32_e32 v117, v102
	v_exp_f32_e32 v116, v118
	v_add_f32_e32 v152, v160, v152
	v_add_f32_e32 v153, v161, v153
	v_pk_add_f32 v[112:113], v[98:99], v[112:113]
	v_exp_f32_e32 v161, v103
	v_exp_f32_e32 v160, v119
	v_exp_f32_e32 v119, v104
	v_exp_f32_e32 v118, v120
	v_pk_add_f32 v[100:101], v[114:115], v[112:113]
	v_add_f32_e32 v152, v162, v152
	v_add_f32_e32 v153, v163, v153
	v_exp_f32_e32 v163, v105
	v_exp_f32_e32 v162, v121
	v_pk_add_f32 v[100:101], v[158:159], v[100:101]
	v_exp_f32_e32 v121, v106
	v_exp_f32_e32 v120, v122
	v_pk_add_f32 v[100:101], v[116:117], v[100:101]
	v_add_f32_e32 v152, v164, v152
	v_add_f32_e32 v153, v165, v153
	v_exp_f32_e32 v165, v107
	v_exp_f32_e32 v164, v123
	v_pk_add_f32 v[100:101], v[160:161], v[100:101]
	v_exp_f32_e32 v123, v108
	v_exp_f32_e32 v122, v124
	v_pk_add_f32 v[100:101], v[118:119], v[100:101]
	v_add_f32_e32 v152, v166, v152
	v_add_f32_e32 v153, v167, v153
	v_exp_f32_e32 v167, v109
	v_exp_f32_e32 v166, v125
	v_pk_add_f32 v[100:101], v[162:163], v[100:101]
	v_exp_f32_e32 v125, v110
	v_exp_f32_e32 v124, v126
	v_pk_add_f32 v[100:101], v[120:121], v[100:101]
	v_add_f32_e32 v152, v168, v152
	v_add_f32_e32 v153, v169, v153
	v_exp_f32_e32 v169, v111
	v_exp_f32_e32 v168, v127
	v_pk_add_f32 v[100:101], v[164:165], v[100:101]
	v_cvt_pk_bf16_f32 v108, v155, v97
	v_pk_add_f32 v[100:101], v[122:123], v[100:101]
	v_cvt_pk_bf16_f32 v110, v115, v159
	v_pk_add_f32 v[100:101], v[166:167], v[100:101]
	v_cvt_pk_bf16_f32 v111, v117, v161
	v_pk_add_f32 v[100:101], v[124:125], v[100:101]
	v_cvt_pk_bf16_f32 v102, v114, v158
	v_pk_add_f32 v[100:101], v[168:169], v[100:101]
	v_cvt_pk_bf16_f32 v103, v116, v160
	v_add_f32_e32 v112, v100, v101
	v_cvt_pk_bf16_f32 v100, v154, v96
	v_cvt_pk_bf16_f32 v104, v119, v163
	v_cvt_pk_bf16_f32 v105, v121, v165
	v_cvt_pk_bf16_f32 v96, v118, v162
	v_cvt_pk_bf16_f32 v97, v120, v164
	ds_read_b128 v[114:117], v151 offset:16384
	ds_read_b128 v[118:121], v151 offset:20480
	v_cvt_pk_bf16_f32 v109, v157, v99
	v_cvt_pk_bf16_f32 v106, v123, v167
	v_cvt_pk_bf16_f32 v107, v125, v169
	s_waitcnt lgkmcnt(0)
	v_mfma_f32_32x32x16_bf16 v[32:47], v[114:117], v[108:111], v[32:47]
	ds_read_b128 v[114:117], v150 offset:20480
	v_cvt_pk_bf16_f32 v101, v156, v98
	v_add_f32_e32 v152, v175, v152
	v_add_f32_e32 v153, v184, v153
	v_add_f32_e32 v152, v185, v152
	v_add_f32_e32 v153, v186, v153
	v_cvt_pk_bf16_f32 v98, v122, v166
	v_mfma_f32_32x32x16_bf16 v[48:63], v[118:121], v[108:111], v[48:63]
	ds_read_b128 v[108:111], v150 offset:16384
	v_cvt_pk_bf16_f32 v99, v124, v168
	v_add_f32_e32 v152, v187, v152
	v_add_f32_e32 v153, v188, v153
	v_add_f32_e32 v152, v189, v152
	v_add_f32_e32 v153, v190, v153
	v_add_f32_e32 v152, v191, v152
	s_waitcnt lgkmcnt(0)
	v_mfma_f32_32x32x16_bf16 v[32:47], v[108:111], v[104:107], v[32:47]
	ds_read_b128 v[108:111], v147 offset:20480
	v_add_f32_e32 v153, v206, v153
	v_add_f32_e32 v152, v210, v152
	v_add_f32_e32 v153, v212, v153
	v_add_f32_e32 v152, v213, v152
	v_add_f32_e32 v153, v214, v153
	v_add_f32_e32 v152, v153, v152
	v_mfma_f32_32x32x16_bf16 v[48:63], v[114:117], v[104:107], v[48:63]
	ds_read_b128 v[104:107], v147 offset:16384
	v_add_f32_e32 v152, 0, v152
	v_add_f32_e32 v184, v152, v112
	s_andn2_b64 vcc, exec, s[42:43]
	s_waitcnt lgkmcnt(0)
	v_mfma_f32_32x32x16_bf16 v[32:47], v[104:107], v[100:103], v[32:47]
	ds_read_b128 v[104:107], v146 offset:20480
	v_mfma_f32_32x32x16_bf16 v[48:63], v[108:111], v[100:103], v[48:63]
	ds_read_b128 v[100:103], v146 offset:16384
	s_waitcnt vmcnt(0)
	s_waitcnt vmcnt(0) lgkmcnt(0)
	s_barrier
	v_mfma_f32_32x32x16_bf16 v[32:47], v[100:103], v[96:99], v[32:47]
	v_mfma_f32_32x32x16_bf16 v[48:63], v[104:107], v[96:99], v[48:63]
	s_cbranch_vccnz .LBB0_204
	s_mov_b64 s[100:101], s[50:51]
	v_readfirstlane_b32 s98, v170
	v_readfirstlane_b32 s99, v171
	v_lshlrev_b32_e32 v222, 1, v192
	v_lshlrev_b32_e32 v227, 1, v140
	v_lshlrev_b32_e32 v228, 1, v142
	v_lshl_add_u64 v[146:147], v[192:193], 1, s[50:51]
	s_mov_b32 s17, 2
	s_movk_i32 s12, 0x3000
	s_mov_b32 s16, 0
	s_movk_i32 s2, 0x6000
.LBB0_191:
	s_add_i32 s8, s13, s17
	s_add_i32 s70, s8, 2
	s_lshl_b64 s[42:43], s[70:71], 12
	s_add_u32 s42, s100, s42
	s_addc_u32 s43, s101, s43
	s_add_i32 s3, s12, 32
	s_add_i32 s10, s3, s98
	s_mov_b32 m0, s10
	s_add_i32 s3, s3, s99
	global_load_lds_dwordx4 v222, s[42:43]
	s_lshl_b64 s[42:43], s[70:71], 7
	s_add_u32 s42, s19, s42
	s_addc_u32 s43, s5, s43
	s_add_i32 m0, s10, 0x1000
	s_addk_i32 s3, 0x1000
	global_load_lds_dwordx4 v227, s[42:43]
	s_mov_b32 m0, s3
	s_mov_b32 s10, s16
	global_load_lds_dwordx4 v228, s[42:43]
	s_add_i32 s42, s10, 32
	v_add_u32_e32 v96, s42, v172
	s_mov_b32 s16, s2
	s_mov_b64 s[2:3], -1
	s_and_b64 vcc, exec, s[28:29]
	v_add_u32_e32 v151, v96, v173
	v_add_u32_e32 v150, v96, v174
	s_cbranch_vccnz .LBB0_193
	ds_read_b128 v[96:99], v151
	ds_read_b128 v[152:155], v150
	s_mov_b64 s[2:3], 0
	s_waitcnt lgkmcnt(0)
	v_mfma_f32_32x32x16_bf16 v[112:127], v[96:99], v[132:135], 0
	ds_read_b128 v[96:99], v151 offset:2048
	v_mfma_f32_32x32x16_bf16 v[112:127], v[152:155], v[128:131], v[112:127]
	ds_read_b128 v[152:155], v150 offset:2048
	s_waitcnt lgkmcnt(0)
	v_mfma_f32_32x32x16_bf16 v[96:111], v[96:99], v[132:135], 0
	v_mfma_f32_32x32x16_bf16 v[96:111], v[152:155], v[128:131], v[96:111]

.LBB0_198:
	v_exp_f32_e32 v166, v88
	v_add_u32_e32 v88, s16, v149
	v_exp_f32_e32 v158, v84
	v_add_u32_e32 v84, v88, v180
	v_exp_f32_e32 v150, v80
	v_exp_f32_e32 v152, v81
	v_exp_f32_e32 v154, v82
	v_exp_f32_e32 v156, v83
	v_exp_f32_e32 v160, v85
	v_exp_f32_e32 v162, v86
	v_exp_f32_e32 v164, v87
	ds_read_b128 v[80:83], v84 offset:4096
	ds_read_b128 v[84:87], v84 offset:8192
	v_exp_f32_e32 v187, v76
	v_exp_f32_e32 v189, v77
	v_exp_f32_e32 v191, v78
	v_exp_f32_e32 v206, v79
	v_cvt_pk_bf16_f32 v76, v150, v152
	v_cvt_pk_bf16_f32 v77, v154, v156
	v_cvt_pk_bf16_f32 v78, v158, v160
	v_cvt_pk_bf16_f32 v79, v162, v164
	v_exp_f32_e32 v168, v89
	v_exp_f32_e32 v175, v90
	s_waitcnt lgkmcnt(0)
	v_mfma_f32_32x32x16_bf16 v[32:47], v[80:83], v[76:79], v[32:47]
	v_add_u32_e32 v80, v88, v181
	v_exp_f32_e32 v177, v91
	v_exp_f32_e32 v186, v92
	v_exp_f32_e32 v188, v93
	v_exp_f32_e32 v190, v94
	v_exp_f32_e32 v192, v95
	v_exp_f32_e32 v167, v72
	v_mfma_f32_32x32x16_bf16 v[48:63], v[84:87], v[76:79], v[48:63]
	ds_read_b128 v[76:79], v80 offset:4096
	ds_read_b128 v[80:83], v80 offset:8192
	v_exp_f32_e32 v169, v73
	v_exp_f32_e32 v176, v74
	v_exp_f32_e32 v185, v75
	v_cvt_pk_bf16_f32 v72, v166, v168
	v_cvt_pk_bf16_f32 v73, v175, v177
	v_cvt_pk_bf16_f32 v74, v186, v188
	v_cvt_pk_bf16_f32 v75, v190, v192
	v_exp_f32_e32 v151, v64
	v_exp_f32_e32 v153, v65
	s_waitcnt lgkmcnt(0)
	v_mfma_f32_32x32x16_bf16 v[32:47], v[76:79], v[72:75], v[32:47]
	v_add_u32_e32 v76, v88, v182
	v_exp_f32_e32 v155, v66
	v_exp_f32_e32 v157, v67
	v_exp_f32_e32 v159, v68
	v_exp_f32_e32 v161, v69
	v_exp_f32_e32 v163, v70
	v_exp_f32_e32 v165, v71
	v_mfma_f32_32x32x16_bf16 v[48:63], v[80:83], v[72:75], v[48:63]
	ds_read_b128 v[72:75], v76 offset:4096
	ds_read_b128 v[76:79], v76 offset:8192
	v_cvt_pk_bf16_f32 v68, v151, v153
	v_cvt_pk_bf16_f32 v69, v155, v157
	v_cvt_pk_bf16_f32 v70, v159, v161
	v_cvt_pk_bf16_f32 v71, v163, v165
	s_add_i32 s70, s8, 3
	s_lshl_b64 s[2:3], s[70:71], 12
	s_waitcnt lgkmcnt(0)
	v_mfma_f32_32x32x16_bf16 v[32:47], v[72:75], v[68:71], v[32:47]
	v_add_u32_e32 v72, v88, v183
	v_cvt_pk_bf16_f32 v64, v167, v169
	v_cvt_pk_bf16_f32 v65, v176, v185
	v_cvt_pk_bf16_f32 v66, v187, v189
	v_cvt_pk_bf16_f32 v67, v191, v206
	s_cmp_lg_u32 32, -1
	v_mfma_f32_32x32x16_bf16 v[48:63], v[76:79], v[68:71], v[48:63]
	ds_read_b128 v[68:71], v72 offset:4096
	ds_read_b128 v[72:75], v72 offset:8192
	s_waitcnt vmcnt(0)
	s_waitcnt vmcnt(0) lgkmcnt(0)
	s_barrier
	v_mfma_f32_32x32x16_bf16 v[32:47], v[68:71], v[64:67], v[32:47]
	v_mfma_f32_32x32x16_bf16 v[48:63], v[72:75], v[64:67], v[48:63]
	s_add_u32 s2, s100, s2
	s_addc_u32 s3, s101, s3
	s_add_i32 s8, s16, 32
	s_add_i32 s43, s8, s98
	s_mov_b32 m0, s43
	s_add_i32 s8, s8, s99
	global_load_lds_dwordx4 v222, s[2:3]
	s_lshl_b64 s[2:3], s[70:71], 7
	s_add_u32 s2, s19, s2
	s_addc_u32 s3, s5, s3
	s_add_i32 m0, s43, 0x1000
	s_addk_i32 s8, 0x1000
	global_load_lds_dwordx4 v227, s[2:3]
	s_mov_b32 m0, s8
	s_add_i32 s8, s12, 32
	global_load_lds_dwordx4 v228, s[2:3]
	v_add_u32_e32 v64, s8, v172
	s_mov_b64 s[2:3], -1
	s_and_b64 vcc, exec, s[28:29]
	v_add_u32_e32 v212, v64, v173
	v_add_u32_e32 v210, v64, v174
	s_cbranch_vccnz .LBB0_200
	ds_read_b128 v[64:67], v212
	ds_read_b128 v[214:217], v210
	s_mov_b64 s[2:3], 0
	s_waitcnt lgkmcnt(0)
	v_mfma_f32_32x32x16_bf16 v[80:95], v[64:67], v[132:135], 0
	ds_read_b128 v[64:67], v212 offset:2048
	v_mfma_f32_32x32x16_bf16 v[80:95], v[214:217], v[128:131], v[80:95]
	ds_read_b128 v[214:217], v210 offset:2048
	s_waitcnt lgkmcnt(0)
	v_mfma_f32_32x32x16_bf16 v[64:79], v[64:67], v[132:135], 0
	v_mfma_f32_32x32x16_bf16 v[64:79], v[214:217], v[128:131], v[64:79]

	.amdhsa_kernel _Z10fwd_kernel6Params
		.amdhsa_group_segment_fixed_size 32
		.amdhsa_private_segment_fixed_size 0
		.amdhsa_kernarg_size 704
		.amdhsa_user_sgpr_count 2
		.amdhsa_user_sgpr_dispatch_ptr 0
		.amdhsa_user_sgpr_queue_ptr 0
		.amdhsa_user_sgpr_kernarg_segment_ptr 1
		.amdhsa_user_sgpr_dispatch_id 0
		.amdhsa_user_sgpr_kernarg_preload_length 0
		.amdhsa_user_sgpr_kernarg_preload_offset 0
		.amdhsa_user_sgpr_private_segment_size 0
		.amdhsa_uses_dynamic_stack 0
		.amdhsa_enable_private_segment 0
		.amdhsa_system_sgpr_workgroup_id_x 1
		.amdhsa_system_sgpr_workgroup_id_y 0
		.amdhsa_system_sgpr_workgroup_id_z 0
		.amdhsa_system_sgpr_workgroup_info 0
		.amdhsa_system_vgpr_workitem_id 2
		.amdhsa_next_free_vgpr 256
		.amdhsa_next_free_sgpr 102
		.amdhsa_accum_offset 256
		.amdhsa_reserve_vcc 1
		.amdhsa_float_round_mode_32 0
		.amdhsa_float_round_mode_16_64 0
		.amdhsa_float_denorm_mode_32 3
		.amdhsa_float_denorm_mode_16_64 3
		.amdhsa_dx10_clamp 1
		.amdhsa_ieee_mode 1
		.amdhsa_fp16_overflow 0
		.amdhsa_tg_split 0
		.amdhsa_exception_fp_ieee_invalid_op 0
		.amdhsa_exception_fp_denorm_src 0
		.amdhsa_exception_fp_ieee_div_zero 0
		.amdhsa_exception_fp_ieee_overflow 0
		.amdhsa_exception_fp_ieee_underflow 0
		.amdhsa_exception_fp_ieee_inexact 0
		.amdhsa_exception_int_div_zero 0
	.end_amdhsa_kernel

.Lfunc_end0:
	.size	_Z10fwd_kernel6Params, .Lfunc_end0-_Z10fwd_kernel6Params
	.set _Z10fwd_kernel6Params.num_vgpr, 256
	.set _Z10fwd_kernel6Params.num_agpr, 0
	.set _Z10fwd_kernel6Params.numbered_sgpr, 102
	.set _Z10fwd_kernel6Params.num_named_barrier, 0
	.set _Z10fwd_kernel6Params.private_seg_size, 0
	.set _Z10fwd_kernel6Params.uses_vcc, 1
	.set _Z10fwd_kernel6Params.uses_flat_scratch, 0
	.set _Z10fwd_kernel6Params.has_dyn_sized_stack, 0
	.set _Z10fwd_kernel6Params.has_recursion, 0
	.set _Z10fwd_kernel6Params.has_indirect_call, 0

amdhsa.kernels:
  - .agpr_count:     0
    .args:
      - .offset:         0
        .size:           448
        .value_kind:     by_value
      - .offset:         448
        .size:           4
        .value_kind:     hidden_block_count_x
      - .offset:         452
        .size:           4
        .value_kind:     hidden_block_count_y
      - .offset:         456
        .size:           4
        .value_kind:     hidden_block_count_z
      - .offset:         460
        .size:           2
        .value_kind:     hidden_group_size_x
      - .offset:         462
        .size:           2
        .value_kind:     hidden_group_size_y
      - .offset:         464
        .size:           2
        .value_kind:     hidden_group_size_z
      - .offset:         466
        .size:           2
        .value_kind:     hidden_remainder_x
      - .offset:         468
        .size:           2
        .value_kind:     hidden_remainder_y
      - .offset:         470
        .size:           2
        .value_kind:     hidden_remainder_z
      - .offset:         488
        .size:           8
        .value_kind:     hidden_global_offset_x
      - .offset:         496
        .size:           8
        .value_kind:     hidden_global_offset_y
      - .offset:         504
        .size:           8
        .value_kind:     hidden_global_offset_z
      - .offset:         512
        .size:           2
        .value_kind:     hidden_grid_dims
      - .offset:         536
        .size:           8
        .value_kind:     hidden_multigrid_sync_arg
      - .offset:         568
        .size:           4
        .value_kind:     hidden_dynamic_lds_size
    .group_segment_fixed_size: 32
    .kernarg_segment_align: 8
    .kernarg_segment_size: 704
    .language:       OpenCL C
    .language_version:
      - 2
      - 0
    .max_flat_workgroup_size: 256
    .name:           _Z10fwd_kernel6Params
    .private_segment_fixed_size: 0
    .sgpr_count:     108
    .sgpr_spill_count: 214
    .symbol:         _Z10fwd_kernel6Params.kd
    .uniform_work_group_size: 1
    .uses_dynamic_stack: false
    .vgpr_count:     256
    .vgpr_spill_count: 0
    .wavefront_size: 64
